# FFN down phase: sample K-slice tasks (and the sample-first order) moved to the workgroups of XCDs 0-3 so each XCD's workgroups stay in step
# baseline (speedup 1.0000x reference)
; __device__ __forceinline__ int bidx() { int b = blockIdx.x; asm volatile("" : "+s"(b)); return b; }
; __device__ __forceinline__ void run_ffn_down(LAS unsigned char* lds, const bf16_t* HID, const bf16_t* WDN, const EpiResid& E, float* PART) {
;     { pg8::StaticOrder S; S.init(T_P, 1024, (int)gridDim.x, bidx());
;       pg8::Gemm g; g.A = HID; g.Bt = WDN; g.M = T_P; g.N = 1024; g.K = 4096; g.ld = 4096;
;       pg8::gemm_phase<EpiResid, pg8::StaticOrder, false>(lds, g, S, E, nullptr); }
;     { const int t = bidx(); OneUnit S; S.valid = t < 128; const int sl = t & 7, u = (t >> 3) & 15; S.pm = 64 + (u >> 2); S.pn = u & 3;
;       pg8::Gemm g; g.A = HID + sl * 512; g.Bt = WDN + sl * 512; g.M = T_ALL; g.N = 1024; g.K = 512; g.ld = 4096;
;       EpiPartial EA; EA.PART = PART + (size_t)sl * 1024 * 1024; EA.ldp = 1024;
;       pg8::gemm_phase<EpiPartial, OneUnit, false>(lds, g, S, EA, nullptr); }
.LBB0_1171:
	s_add_u32 s45, s10, 0x5500000
	s_addc_u32 s46, s42, 0
	s_add_u32 s47, s10, 0x1800000
	s_addc_u32 s48, s42, 0
	s_bitcmp1_b32 s90, 2
	s_cbranch_scc1 .Lp13_main
	v_writelane_b32 v255, s0, 0
	v_writelane_b32 v255, s1, 1
	v_writelane_b32 v255, s12, 2
	v_writelane_b32 v255, s13, 3
	v_writelane_b32 v255, s20, 4
	v_writelane_b32 v255, s21, 5
	v_writelane_b32 v255, s22, 6
	v_writelane_b32 v255, s24, 7
	v_writelane_b32 v255, s34, 8
	v_writelane_b32 v255, s35, 9
	s_mov_b32 s0, 1
	v_writelane_b32 v242, s0, 61
	s_branch .LBB0_1203

; __device__ __forceinline__ int bidx() { int b = blockIdx.x; asm volatile("" : "+s"(b)); return b; }
; __device__ __forceinline__ void run_ffn_down(LAS unsigned char* lds, const bf16_t* HID, const bf16_t* WDN, const EpiResid& E, float* PART) {
;     ...
;     { const int t = bidx(); OneUnit S; S.valid = t < 128; const int sl = t & 7, u = (t >> 3) & 15; S.pm = 64 + (u >> 2); S.pn = u & 3;
;       pg8::Gemm g; g.A = HID + sl * 512; g.Bt = WDN + sl * 512; g.M = T_ALL; g.N = 1024; g.K = 512; g.ld = 4096;
;       EpiPartial EA; EA.PART = PART + (size_t)sl * 1024 * 1024; EA.ldp = 1024;
;       pg8::gemm_phase<EpiPartial, OneUnit, false>(lds, g, S, EA, nullptr); }
.LBB0_1203:
	v_readlane_b32 s4, v242, 61
	s_cmp_eq_u32 s4, 2
	s_cbranch_scc1 .Lp13_skipB
	s_lshr_b32 s22, s90, 3
	s_lshl_b32 s22, s22, 2
	s_and_b32 s4, s90, 7
	s_add_i32 s22, s22, s4
	s_bitcmp1_b32 s90, 2
	s_cselect_b32 s4, 0x100, s22
	s_waitcnt lgkmcnt(0)
	v_mov_b32_e32 v12, v184
	s_cmpk_gt_i32 s4, 0x7f
	s_nop 0
	v_readfirstlane_b32 s22, v12
	s_cbranch_scc1 .LBB0_1211
	v_lshlrev_b32_e32 v0, 4, v12
	v_add_u32_e32 v1, 0x2000, v0
	v_ashrrev_i32_e32 v2, 31, v1
	v_lshrrev_b32_e32 v2, 22, v2
	v_add_u32_e32 v2, v1, v2
	v_ashrrev_i32_e32 v8, 10, v2
	v_mul_i32_i24_e32 v2, 0x400, v8
	v_sub_u32_e32 v1, v1, v2
	v_lshrrev_b32_e32 v2, 4, v1
	v_bitop3_b32 v1, v2, v1, 32 bitop3:0x6c
	v_ashrrev_i32_e32 v2, 31, v1
	v_lshrrev_b32_e32 v2, 26, v2
	v_add_u32_e32 v2, v1, v2
	v_ashrrev_i32_e32 v9, 6, v2
	v_and_b32_e32 v2, 0xc0, v2
	v_sub_u32_e32 v1, v1, v2
	v_ashrrev_i16_sdwa v1, v188, sext(v1) dst_sel:DWORD dst_unused:UNUSED_PAD src0_sel:DWORD src1_sel:BYTE_0
	v_bfe_i32 v11, v1, 0, 16
	v_bfe_i32 v1, v12, 27, 1
	v_lshrrev_b32_e32 v1, 22, v1
	v_add_u32_e32 v1, v0, v1
	v_and_b32_e32 v1, 0xfffffc00, v1
	v_sub_u32_e32 v0, v0, v1
	v_lshrrev_b32_e32 v1, 4, v0
	s_and_b32 s25, s4, 7
	s_bfe_u32 s0, s4, 0x20005
	s_ashr_i32 s6, s22, 6
	v_bitop3_b32 v0, v1, v0, 32 bitop3:0x6c
	v_ashrrev_i32_e32 v2, 31, v12
	s_or_b32 s24, s0, 64
	s_bfe_u32 s23, s4, 0x20003
	s_ashr_i32 s7, s22, 8
	s_lshl_b32 s26, s6, 10
	s_lshl_b32 s5, s25, 10
	v_lshlrev_b32_e32 v3, 3, v8
	v_ashrrev_i32_e32 v1, 31, v0
	v_lshrrev_b32_e32 v2, 26, v2
	s_add_u32 s0, s47, s5
	v_and_b32_e32 v3, 0x7fff0, v3
	v_lshlrev_b32_e32 v4, 5, v8
	v_lshrrev_b32_e32 v1, 26, v1
	v_add_u32_e32 v2, v12, v2
	s_addc_u32 s1, s48, 0
	v_add_u32_e32 v3, v9, v3
	v_and_b32_e32 v10, 32, v4
	v_add_u32_e32 v1, v0, v1
	v_ashrrev_i32_e32 v14, 6, v2
	s_add_u32 s2, s45, s5
	v_lshl_or_b32 v3, v3, 12, v10
	v_ashrrev_i32_e32 v13, 6, v1
	v_lshlrev_b32_e32 v2, 3, v14
	v_and_b32_e32 v1, 0xc0, v1
	s_addc_u32 s3, s46, 0
	v_add_lshl_u32 v148, v3, v11, 1
	v_and_b32_e32 v2, 0x7fff0, v2
	v_lshlrev_b32_e32 v3, 5, v14
	v_sub_u32_e32 v0, v0, v1
	s_lshl_b32 s12, s24, 21
	s_lshl_b32 s13, s23, 21
	v_add_u32_e32 v2, v13, v2
	v_and_b32_e32 v15, 32, v3
	v_ashrrev_i16_sdwa v0, v188, sext(v0) dst_sel:DWORD dst_unused:UNUSED_PAD src0_sel:DWORD src1_sel:BYTE_0
	s_add_u32 s0, s0, s13
	v_lshl_or_b32 v2, v2, 12, v15
	v_bfe_i32 v16, v0, 0, 16
	s_addc_u32 s1, s1, 0
	s_add_i32 s27, s26, 0
	v_add_lshl_u32 v128, v2, v16, 1
	s_add_i32 m0, s27, 0x10000
	v_mov_b32_e32 v149, v129
	global_load_lds_dwordx4 v128, s[0:1]
	s_add_i32 m0, s27, 0x12000
	s_add_u32 s2, s2, s12
	global_load_lds_dwordx4 v148, s[0:1]
	s_addc_u32 s3, s3, 0
	s_mov_b32 m0, s27
	s_add_i32 s30, s27, 0x2000
	global_load_lds_dwordx4 v128, s[2:3]
	s_mov_b32 m0, s30
	s_add_u32 s12, s0, 0x100000
	global_load_lds_dwordx4 v148, s[2:3]
	s_addc_u32 s13, s1, 0
	s_add_i32 m0, s27, 0x14000
	v_lshl_add_u64 v[6:7], s[0:1], 0, v[128:129]
	global_load_lds_dwordx4 v128, s[12:13]
	s_add_i32 m0, s27, 0x16000
	v_lshl_add_u64 v[4:5], s[0:1], 0, v[148:149]
	global_load_lds_dwordx4 v148, s[12:13]
	s_add_u32 s12, s2, 0x100000
	s_addc_u32 s13, s3, 0
	s_add_i32 s31, s27, 0x4000
	s_mov_b32 m0, s31
	s_add_i32 s34, s27, 0x6000
	global_load_lds_dwordx4 v128, s[12:13]
	s_mov_b32 m0, s34
	v_lshl_add_u64 v[2:3], s[2:3], 0, v[128:129]
	global_load_lds_dwordx4 v148, s[12:13]
	s_cmp_lg_u32 s7, 1
	v_lshl_add_u64 v[0:1], s[2:3], 0, v[148:149]
	s_cbranch_scc1 .LBB0_1206
	s_barrier
